# v6 + attention item epilogue: g_att gain quads loaded once per workgroup into spare VGPRs, 16 (MQ=4) / 8 (MQ=2) per-item reload + vmcnt(0) round trips removed
# speedup vs baseline: 1.0031x; 1.0031x over previous
.LBB0_434:
	s_lshl_b64 s[92:93], s[14:15], 1
	s_add_u32 s4, s70, s92
	s_mul_i32 s3, s68, 0xffffd300
	s_addc_u32 s5, s71, s93
	s_add_i32 s86, s58, s3
	s_mul_i32 s6, s14, 0x10800
	s_mul_hi_i32 s3, s14, 0x10800
	s_add_u32 s6, s76, s6
	v_readlane_b32 s36, v249, 57
	s_addc_u32 s7, s77, s3
	s_lshl_b64 s[8:9], s[14:15], 2
	v_readlane_b32 s40, v249, 61
	v_readlane_b32 s41, v249, 62
	s_add_u32 s8, s40, s8
	v_readlane_b32 s42, v249, 63
	s_addc_u32 s9, s41, s9
	v_readlane_b32 s43, v248, 0
	s_add_u32 s42, s12, s92
	s_getreg_b32 s3, hwreg(HW_REG_XCC_ID, 0, 4)
	s_addc_u32 s43, s13, s93
	s_and_b32 s3, s3, 7
	s_lshl_b32 s15, s3, 8
	s_add_u32 s40, s18, s15
	s_addc_u32 s41, s19, 0
	s_add_u32 s60, s24, 0x1a20400
	s_addc_u32 s61, s25, 0
	s_add_u32 s64, s24, 0x1a20500
	s_addc_u32 s65, s25, 0
	s_add_u32 s66, s24, 0x1a20600
	s_addc_u32 s67, s25, 0
	s_add_u32 s74, s24, 0x1a20700
	s_addc_u32 s75, s25, 0
	s_add_u32 s76, s24, 0x1a20800
	v_lshlrev_b32_e32 v0, 1, v185
	s_addc_u32 s77, s25, 0
	v_and_b32_e32 v226, 24, v0
	v_and_b32_e32 v227, 3, v152
	s_add_u32 s78, s24, 0x1a20900
	v_lshl_add_u64 v[188:189], s[4:5], 0, v[186:187]
	v_or_b32_e32 v228, v226, v227
	s_movk_i32 s4, 0xa00
	v_mov_b32_e32 v1, 0x2800
	s_addc_u32 s79, s25, 0
	v_mad_u32_u24 v2, v228, s4, v1
	v_mul_u32_u24_e32 v1, 0x8400, v185
	s_add_u32 s80, s24, 0x1a20a00
	v_mul_u32_u24_e32 v0, 0xa00, v228
	v_mov_b32_e32 v197, 0
	v_lshl_add_u64 v[190:191], s[6:7], 0, v[186:187]
	v_lshlrev_b32_e32 v196, 1, v1
	v_lshlrev_b32_e32 v4, 2, v153
	s_addc_u32 s81, s25, 0
	v_readlane_b32 s39, v249, 60
	v_lshl_add_u64 v[198:199], v[190:191], 0, v[196:197]
	v_ashrrev_i32_e32 v5, 31, v4
	s_add_u32 s82, s24, 0x1a20b00
	v_lshlrev_b32_e32 v196, 1, v0
	s_mov_b32 s39, 0
	v_sub_u32_e32 v229, v82, v185
	v_cmp_gt_u32_e64 s[6:7], 16, v152
	v_lshl_add_u32 v224, v152, 2, s69
	v_lshl_add_u64 v[192:193], v[4:5], 2, s[8:9]
	v_lshl_add_u32 v225, v185, 2, 0
	v_lshl_add_u64 v[194:195], v[4:5], 1, s[42:43]
	s_addc_u32 s83, s25, 0
	v_lshl_add_u64 v[200:201], v[188:189], 0, v[196:197]
	v_lshlrev_b32_e32 v202, 1, v2
	v_lshlrev_b32_e32 v204, 1, v0
	s_movk_i32 s15, 0xff80
	v_mov_b32_e32 v230, 0x358637bd
	v_mov_b32_e32 v231, 0x1400
	v_readlane_b32 s37, v249, 58
	v_readlane_b32 s38, v249, 59
	v_readlane_b32 s44, v248, 1
	v_readlane_b32 s45, v248, 2
	v_readlane_b32 s46, v248, 3
	v_readlane_b32 s47, v248, 4
	v_readlane_b32 s48, v248, 5
	v_readlane_b32 s49, v248, 6
	v_readlane_b32 s50, v248, 7
	v_readlane_b32 s51, v248, 8
	global_load_dwordx4 v[238:241], v[192:193], off
	global_load_dwordx4 v[242:245], v[192:193], off offset:64
	global_load_dwordx4 v[250:253], v[192:193], off offset:128
	global_load_dwordx2 v[246:247], v[192:193], off offset:192
	global_load_dwordx2 v[254:255], v[192:193], off offset:200
	s_waitcnt vmcnt(0)
	s_branch .LBB0_436
.LBB0_435:
	s_or_b64 exec, exec, s[4:5]
	v_add_u32_e32 v86, 0x2000, v225
	s_waitcnt lgkmcnt(0)
	s_barrier
	ds_read2_b32 v[68:69], v86 offset1:16
	ds_read2_b32 v[70:71], v86 offset0:64 offset1:80
	ds_read2_b32 v[72:73], v86 offset0:128 offset1:144
	ds_read2_b32 v[74:75], v86 offset0:192 offset1:208
	s_waitcnt lgkmcnt(3)
	v_add_f32_e32 v8, 0, v68
	s_waitcnt lgkmcnt(2)
	v_add_f32_e32 v8, v8, v70
	v_add_u32_e32 v70, 0x2400, v225
	ds_read2_b32 v[76:77], v70 offset1:16
	ds_read2_b32 v[78:79], v70 offset0:64 offset1:80
	ds_read2_b32 v[80:81], v70 offset0:128 offset1:144
	s_waitcnt lgkmcnt(4)
	v_add_f32_e32 v8, v8, v72
	ds_read2_b32 v[82:83], v70 offset0:192 offset1:208
	s_waitcnt lgkmcnt(4)
	v_add_f32_e32 v8, v8, v74
	s_waitcnt lgkmcnt(3)
	v_add_f32_e32 v8, v8, v76
	s_waitcnt lgkmcnt(2)
	v_add_f32_e32 v8, v8, v78
	s_waitcnt lgkmcnt(1)
	v_add_f32_e32 v8, v8, v80
	s_waitcnt lgkmcnt(0)
	v_add_f32_e32 v8, v8, v82
	v_fmamk_f32 v8, v8, 0x3b000000, v230
	v_rsq_f32_e32 v68, v8
	v_lshlrev_b64 v[8:9], 11, v[196:197]
	v_lshl_add_u64 v[84:85], v[194:195], 0, v[8:9]
	v_pk_mul_f32 v[64:65], v[64:65], v[68:69] op_sel_hi:[1,0]
	v_pk_mul_f32 v[66:67], v[66:67], v[68:69] op_sel_hi:[1,0]
	v_pk_mul_f32 v[60:61], v[60:61], v[68:69] op_sel_hi:[1,0]
	v_pk_mul_f32 v[62:63], v[62:63], v[68:69] op_sel_hi:[1,0]
	v_pk_mul_f32 v[56:57], v[56:57], v[68:69] op_sel_hi:[1,0]
	v_pk_mul_f32 v[58:59], v[58:59], v[68:69] op_sel_hi:[1,0]
	v_pk_mul_f32 v[52:53], v[52:53], v[68:69] op_sel_hi:[1,0]
	v_pk_mul_f32 v[54:55], v[54:55], v[68:69] op_sel_hi:[1,0]
	v_pk_mul_f32 v[10:11], v[240:241], v[64:65]
	v_pk_mul_f32 v[8:9], v[238:239], v[66:67]
	s_nop 0
	v_cvt_pk_bf16_f32 v8, v8, v9
	v_cvt_pk_bf16_f32 v9, v10, v11
	global_store_dwordx2 v[84:85], v[8:9], off
	s_nop 1
	v_pk_mul_f32 v[10:11], v[244:245], v[60:61]
	v_pk_mul_f32 v[8:9], v[242:243], v[62:63]
	s_nop 0
	v_cvt_pk_bf16_f32 v8, v8, v9
	v_cvt_pk_bf16_f32 v9, v10, v11
	global_store_dwordx2 v[84:85], v[8:9], off offset:32
	s_nop 1
	v_pk_mul_f32 v[10:11], v[252:253], v[56:57]
	v_pk_mul_f32 v[8:9], v[250:251], v[58:59]
	s_nop 0
	v_cvt_pk_bf16_f32 v8, v8, v9
	v_cvt_pk_bf16_f32 v9, v10, v11
	global_store_dwordx2 v[84:85], v[8:9], off offset:64
	s_nop 1
	v_pk_mul_f32 v[10:11], v[254:255], v[52:53]
	v_pk_mul_f32 v[8:9], v[246:247], v[54:55]
	s_nop 0
	v_cvt_pk_bf16_f32 v8, v8, v9
	v_cvt_pk_bf16_f32 v9, v10, v11
	global_store_dwordx2 v[84:85], v[8:9], off offset:96
	s_nop 1
	v_add_f32_e32 v8, 0, v69
	v_add_f32_e32 v8, v8, v71
	v_add_f32_e32 v8, v8, v73
	v_add_f32_e32 v8, v8, v75
	v_add_f32_e32 v8, v8, v77
	v_add_f32_e32 v8, v8, v79
	v_add_f32_e32 v8, v8, v81
	v_add_f32_e32 v8, v8, v83
	v_fmamk_f32 v8, v8, 0x3b000000, v230
	v_rsq_f32_e32 v52, v8
	v_or_b32_e32 v8, 16, v196
	v_mov_b32_e32 v9, v197
	v_lshlrev_b64 v[8:9], 11, v[8:9]
	v_lshl_add_u64 v[54:55], v[194:195], 0, v[8:9]
	v_pk_mul_f32 v[48:49], v[48:49], v[52:53] op_sel_hi:[1,0]
	v_pk_mul_f32 v[50:51], v[50:51], v[52:53] op_sel_hi:[1,0]
	v_pk_mul_f32 v[46:47], v[46:47], v[52:53] op_sel_hi:[1,0]
	v_pk_mul_f32 v[44:45], v[44:45], v[52:53] op_sel_hi:[1,0]
	v_pk_mul_f32 v[40:41], v[40:41], v[52:53] op_sel_hi:[1,0]
	v_pk_mul_f32 v[42:43], v[42:43], v[52:53] op_sel_hi:[1,0]
	v_pk_mul_f32 v[36:37], v[36:37], v[52:53] op_sel_hi:[1,0]
	v_pk_mul_f32 v[38:39], v[38:39], v[52:53] op_sel_hi:[1,0]
	v_pk_mul_f32 v[10:11], v[240:241], v[48:49]
	v_pk_mul_f32 v[8:9], v[238:239], v[50:51]
	ds_read2_b32 v[48:49], v70 offset0:160 offset1:176
	v_cvt_pk_bf16_f32 v8, v8, v9
	v_cvt_pk_bf16_f32 v9, v10, v11
	global_store_dwordx2 v[54:55], v[8:9], off
	s_nop 1
	ds_read2_b32 v[50:51], v70 offset0:224 offset1:240
	v_pk_mul_f32 v[10:11], v[244:245], v[46:47]
	v_pk_mul_f32 v[8:9], v[242:243], v[44:45]
	ds_read2_b32 v[44:45], v70 offset0:32 offset1:48
	v_cvt_pk_bf16_f32 v8, v8, v9
	v_cvt_pk_bf16_f32 v9, v10, v11
	global_store_dwordx2 v[54:55], v[8:9], off offset:32
	s_nop 1
	ds_read2_b32 v[46:47], v70 offset0:96 offset1:112
	v_pk_mul_f32 v[10:11], v[252:253], v[40:41]
	v_pk_mul_f32 v[8:9], v[250:251], v[42:43]
	ds_read2_b32 v[40:41], v86 offset0:160 offset1:176
	v_cvt_pk_bf16_f32 v8, v8, v9
	v_cvt_pk_bf16_f32 v9, v10, v11
	global_store_dwordx2 v[54:55], v[8:9], off offset:64
	s_nop 1
	ds_read2_b32 v[42:43], v86 offset0:224 offset1:240
	v_pk_mul_f32 v[10:11], v[254:255], v[36:37]
	v_pk_mul_f32 v[8:9], v[246:247], v[38:39]
	v_or_b32_e32 v36, 32, v196
	v_cvt_pk_bf16_f32 v8, v8, v9
	v_cvt_pk_bf16_f32 v9, v10, v11
	v_mov_b32_e32 v37, v197
	global_store_dwordx2 v[54:55], v[8:9], off offset:96
	s_nop 1
	v_lshlrev_b64 v[36:37], 11, v[36:37]
	v_lshl_add_u64 v[52:53], v[194:195], 0, v[36:37]
	ds_read2_b32 v[8:9], v86 offset0:32 offset1:48
	ds_read2_b32 v[10:11], v86 offset0:96 offset1:112
	v_or_b32_e32 v196, 48, v196
	s_waitcnt lgkmcnt(1)
	v_add_f32_e32 v8, 0, v8
	s_waitcnt lgkmcnt(0)
	v_add_f32_e32 v8, v8, v10
	v_add_f32_e32 v8, v8, v40
	v_add_f32_e32 v8, v8, v42
	v_add_f32_e32 v8, v8, v44
	v_add_f32_e32 v8, v8, v46
	v_add_f32_e32 v8, v8, v48
	v_add_f32_e32 v8, v8, v50
	v_fmamk_f32 v8, v8, 0x3b000000, v230
	v_rsq_f32_e32 v8, v8
	s_nop 0
	v_pk_mul_f32 v[32:33], v[32:33], v[8:9] op_sel_hi:[1,0]
	v_pk_mul_f32 v[34:35], v[34:35], v[8:9] op_sel_hi:[1,0]
	v_pk_mul_f32 v[30:31], v[30:31], v[8:9] op_sel_hi:[1,0]
	v_pk_mul_f32 v[28:29], v[28:29], v[8:9] op_sel_hi:[1,0]
	v_pk_mul_f32 v[24:25], v[24:25], v[8:9] op_sel_hi:[1,0]
	v_pk_mul_f32 v[26:27], v[26:27], v[8:9] op_sel_hi:[1,0]
	v_pk_mul_f32 v[20:21], v[20:21], v[8:9] op_sel_hi:[1,0]
	v_pk_mul_f32 v[22:23], v[22:23], v[8:9] op_sel_hi:[1,0]
	v_add_f32_e32 v8, 0, v9
	v_add_f32_e32 v8, v8, v11
	v_add_f32_e32 v8, v8, v41
	v_add_f32_e32 v8, v8, v43
	v_add_f32_e32 v8, v8, v45
	v_add_f32_e32 v8, v8, v47
	v_add_f32_e32 v8, v8, v49
	v_add_f32_e32 v8, v8, v51
	v_fmamk_f32 v8, v8, 0x3b000000, v230
	v_pk_mul_f32 v[32:33], v[240:241], v[32:33]
	v_pk_mul_f32 v[34:35], v[238:239], v[34:35]
	s_nop 0
	v_cvt_pk_bf16_f32 v34, v34, v35
	v_cvt_pk_bf16_f32 v35, v32, v33
	global_store_dwordx2 v[52:53], v[34:35], off
	s_nop 1
	v_pk_mul_f32 v[30:31], v[244:245], v[30:31]
	v_pk_mul_f32 v[28:29], v[242:243], v[28:29]
	s_nop 0
	v_cvt_pk_bf16_f32 v28, v28, v29
	v_cvt_pk_bf16_f32 v29, v30, v31
	global_store_dwordx2 v[52:53], v[28:29], off offset:32
	s_nop 1
	v_pk_mul_f32 v[24:25], v[252:253], v[24:25]
	v_pk_mul_f32 v[26:27], v[250:251], v[26:27]
	s_nop 0
	v_cvt_pk_bf16_f32 v26, v26, v27
	v_cvt_pk_bf16_f32 v27, v24, v25
	global_store_dwordx2 v[52:53], v[26:27], off offset:64
	s_nop 1
	v_pk_mul_f32 v[20:21], v[254:255], v[20:21]
	v_pk_mul_f32 v[22:23], v[246:247], v[22:23]
	s_nop 0
	v_cvt_pk_bf16_f32 v22, v22, v23
	v_cvt_pk_bf16_f32 v23, v20, v21
	global_store_dwordx2 v[52:53], v[22:23], off offset:96
	s_nop 1
	v_rsq_f32_e32 v20, v8
	v_lshlrev_b64 v[8:9], 11, v[196:197]
	v_lshl_add_u64 v[22:23], v[194:195], 0, v[8:9]
	v_pk_mul_f32 v[16:17], v[16:17], v[20:21] op_sel_hi:[1,0]
	v_pk_mul_f32 v[18:19], v[18:19], v[20:21] op_sel_hi:[1,0]
	v_pk_mul_f32 v[14:15], v[14:15], v[20:21] op_sel_hi:[1,0]
	v_pk_mul_f32 v[12:13], v[12:13], v[20:21] op_sel_hi:[1,0]
	v_pk_mul_f32 v[4:5], v[4:5], v[20:21] op_sel_hi:[1,0]
	v_pk_mul_f32 v[6:7], v[6:7], v[20:21] op_sel_hi:[1,0]
	v_pk_mul_f32 v[2:3], v[2:3], v[20:21] op_sel_hi:[1,0]
	v_pk_mul_f32 v[0:1], v[0:1], v[20:21] op_sel_hi:[1,0]
	v_pk_mul_f32 v[10:11], v[240:241], v[16:17]
	v_pk_mul_f32 v[8:9], v[238:239], v[18:19]
	s_nop 0
	v_cvt_pk_bf16_f32 v8, v8, v9
	v_cvt_pk_bf16_f32 v9, v10, v11
	global_store_dwordx2 v[22:23], v[8:9], off
	s_nop 1
	v_pk_mul_f32 v[10:11], v[244:245], v[14:15]
	v_pk_mul_f32 v[8:9], v[242:243], v[12:13]
	s_nop 0
	v_cvt_pk_bf16_f32 v8, v8, v9
	v_cvt_pk_bf16_f32 v9, v10, v11
	global_store_dwordx2 v[22:23], v[8:9], off offset:32
	s_nop 1
	v_pk_mul_f32 v[4:5], v[252:253], v[4:5]
	v_pk_mul_f32 v[6:7], v[250:251], v[6:7]
	s_nop 0
	v_cvt_pk_bf16_f32 v6, v6, v7
	v_cvt_pk_bf16_f32 v7, v4, v5
	global_store_dwordx2 v[22:23], v[6:7], off offset:64
	s_nop 1
	v_pk_mul_f32 v[2:3], v[254:255], v[2:3]
	v_pk_mul_f32 v[0:1], v[246:247], v[0:1]
	s_nop 0
	v_cvt_pk_bf16_f32 v0, v0, v1
	v_cvt_pk_bf16_f32 v1, v2, v3
	global_store_dwordx2 v[22:23], v[0:1], off offset:96
	s_nop 1
	s_barrier

.LBB0_483:
	s_or_b64 exec, exec, s[4:5]
	v_add_u32_e32 v8, 0x2000, v225
	s_waitcnt lgkmcnt(0)
	s_barrier
	ds_read2_b32 v[36:37], v8 offset1:16
	ds_read2_b32 v[38:39], v8 offset0:64 offset1:80
	ds_read2_b32 v[40:41], v8 offset0:128 offset1:144
	ds_read2_b32 v[42:43], v8 offset0:192 offset1:208
	s_mov_b64 s[4:5], 0
	s_waitcnt lgkmcnt(3)
	v_add_f32_e32 v9, 0, v36
	s_waitcnt lgkmcnt(2)
	v_add_f32_e32 v9, v9, v38
	s_waitcnt lgkmcnt(1)
	v_add_f32_e32 v9, v9, v40
	s_waitcnt lgkmcnt(0)
	v_add_f32_e32 v8, v9, v42
	v_add_u32_e32 v9, 0x2400, v225
	ds_read2_b32 v[44:45], v9 offset1:16
	ds_read2_b32 v[46:47], v9 offset0:64 offset1:80
	ds_read2_b32 v[48:49], v9 offset0:128 offset1:144
	ds_read2_b32 v[50:51], v9 offset0:192 offset1:208
	s_waitcnt lgkmcnt(3)
	v_add_f32_e32 v8, v8, v44
	s_waitcnt lgkmcnt(2)
	v_add_f32_e32 v8, v8, v46
	s_waitcnt lgkmcnt(1)
	v_add_f32_e32 v8, v8, v48
	s_waitcnt lgkmcnt(0)
	v_add_f32_e32 v8, v8, v50
	v_fmamk_f32 v8, v8, 0x3b000000, v209
	v_rsq_f32_e32 v36, v8
	v_lshlrev_b64 v[8:9], 11, v[140:141]
	v_lshl_add_u64 v[52:53], v[194:195], 0, v[8:9]
	v_pk_mul_f32 v[32:33], v[32:33], v[36:37] op_sel_hi:[1,0]
	v_pk_mul_f32 v[34:35], v[34:35], v[36:37] op_sel_hi:[1,0]
	v_pk_mul_f32 v[28:29], v[28:29], v[36:37] op_sel_hi:[1,0]
	v_pk_mul_f32 v[30:31], v[30:31], v[36:37] op_sel_hi:[1,0]
	v_pk_mul_f32 v[24:25], v[24:25], v[36:37] op_sel_hi:[1,0]
	v_pk_mul_f32 v[26:27], v[26:27], v[36:37] op_sel_hi:[1,0]
	v_pk_mul_f32 v[20:21], v[20:21], v[36:37] op_sel_hi:[1,0]
	v_pk_mul_f32 v[22:23], v[22:23], v[36:37] op_sel_hi:[1,0]
	v_pk_mul_f32 v[10:11], v[240:241], v[32:33]
	v_pk_mul_f32 v[8:9], v[238:239], v[34:35]
	s_nop 0
	v_cvt_pk_bf16_f32 v8, v8, v9
	v_cvt_pk_bf16_f32 v9, v10, v11
	global_store_dwordx2 v[52:53], v[8:9], off
	s_nop 1
	v_pk_mul_f32 v[10:11], v[244:245], v[28:29]
	v_pk_mul_f32 v[8:9], v[242:243], v[30:31]
	s_nop 0
	v_cvt_pk_bf16_f32 v8, v8, v9
	v_cvt_pk_bf16_f32 v9, v10, v11
	global_store_dwordx2 v[52:53], v[8:9], off offset:32
	s_nop 1
	v_pk_mul_f32 v[10:11], v[252:253], v[24:25]
	v_pk_mul_f32 v[8:9], v[250:251], v[26:27]
	s_nop 0
	v_cvt_pk_bf16_f32 v8, v8, v9
	v_cvt_pk_bf16_f32 v9, v10, v11
	global_store_dwordx2 v[52:53], v[8:9], off offset:64
	s_nop 1
	v_pk_mul_f32 v[10:11], v[254:255], v[20:21]
	v_pk_mul_f32 v[8:9], v[246:247], v[22:23]
	s_nop 0
	v_cvt_pk_bf16_f32 v8, v8, v9
	v_cvt_pk_bf16_f32 v9, v10, v11
	global_store_dwordx2 v[52:53], v[8:9], off offset:96
	s_nop 1
	v_add_f32_e32 v8, 0, v37
	v_add_f32_e32 v8, v8, v39
	v_add_f32_e32 v8, v8, v41
	v_add_f32_e32 v8, v8, v43
	v_add_f32_e32 v8, v8, v45
	v_add_f32_e32 v8, v8, v47
	v_add_f32_e32 v8, v8, v49
	v_add_f32_e32 v8, v8, v51
	v_fmamk_f32 v8, v8, 0x3b000000, v209
	v_rsq_f32_e32 v20, v8
	v_or_b32_e32 v8, 16, v140
	v_ashrrev_i32_e32 v9, 31, v8
	v_lshlrev_b64 v[8:9], 11, v[8:9]
	v_lshl_add_u64 v[22:23], v[194:195], 0, v[8:9]
	v_pk_mul_f32 v[16:17], v[16:17], v[20:21] op_sel_hi:[1,0]
	v_pk_mul_f32 v[18:19], v[18:19], v[20:21] op_sel_hi:[1,0]
	v_pk_mul_f32 v[14:15], v[14:15], v[20:21] op_sel_hi:[1,0]
	v_pk_mul_f32 v[12:13], v[12:13], v[20:21] op_sel_hi:[1,0]
	v_pk_mul_f32 v[4:5], v[4:5], v[20:21] op_sel_hi:[1,0]
	v_pk_mul_f32 v[6:7], v[6:7], v[20:21] op_sel_hi:[1,0]
	v_pk_mul_f32 v[2:3], v[2:3], v[20:21] op_sel_hi:[1,0]
	v_pk_mul_f32 v[0:1], v[0:1], v[20:21] op_sel_hi:[1,0]
	v_pk_mul_f32 v[10:11], v[240:241], v[16:17]
	v_pk_mul_f32 v[8:9], v[238:239], v[18:19]
	s_nop 0
	v_cvt_pk_bf16_f32 v8, v8, v9
	v_cvt_pk_bf16_f32 v9, v10, v11
	global_store_dwordx2 v[22:23], v[8:9], off
	s_nop 1
	v_pk_mul_f32 v[10:11], v[244:245], v[14:15]
	v_pk_mul_f32 v[8:9], v[242:243], v[12:13]
	s_nop 0
	v_cvt_pk_bf16_f32 v8, v8, v9
	v_cvt_pk_bf16_f32 v9, v10, v11
	global_store_dwordx2 v[22:23], v[8:9], off offset:32
	s_nop 1
	v_pk_mul_f32 v[4:5], v[252:253], v[4:5]
	v_pk_mul_f32 v[6:7], v[250:251], v[6:7]
	s_nop 0
	v_cvt_pk_bf16_f32 v6, v6, v7
	v_cvt_pk_bf16_f32 v7, v4, v5
	global_store_dwordx2 v[22:23], v[6:7], off offset:64
	s_nop 1
	v_pk_mul_f32 v[2:3], v[254:255], v[2:3]
	v_pk_mul_f32 v[0:1], v[246:247], v[0:1]
	s_nop 0
	v_cvt_pk_bf16_f32 v0, v0, v1
	v_cvt_pk_bf16_f32 v1, v2, v3
	global_store_dwordx2 v[22:23], v[0:1], off offset:96
	s_nop 1
	s_barrier
